# ff1 GEMM epilogue: first chunk waits only for its row statistic (counted vmcnt) and for the column vectors at their first use
# speedup vs baseline: 1.0046x; 1.0046x over previous
.LBB0_756:
	v_lshl_add_u32 v164, s4, 8, v168
	v_ashrrev_i32_e32 v165, 31, v164
	v_lshl_add_u64 v[160:161], v[164:165], 2, s[12:13]
	global_load_dword v177, v[160:161], off
	global_load_dword v230, v[160:161], off offset:64
	global_load_dword v231, v[160:161], off offset:128
	global_load_dword v232, v[160:161], off offset:192
	global_load_dword v233, v[160:161], off offset:512
	global_load_dword v234, v[160:161], off offset:576
	global_load_dword v235, v[160:161], off offset:640
	global_load_dword v236, v[160:161], off offset:704
	s_ashr_i32 s4, s4, 4
	s_ashr_i32 s5, s4, 31
	s_lshl_b64 s[4:5], s[4:5], 14
	v_lshl_or_b32 v162, s3, 8, v170
	s_add_u32 s4, s67, s4
	v_ashrrev_i32_e32 v163, 31, v162
	s_addc_u32 s5, s68, s5
	v_lshl_add_u64 v[88:89], v[162:163], 2, s[4:5]
	global_load_dwordx4 v[100:103], v[88:89], off
	global_load_dwordx4 v[96:99], v[88:89], off offset:16
	global_load_dwordx4 v[92:95], v[88:89], off offset:512
	s_nop 0
	global_load_dwordx4 v[88:91], v[88:89], off offset:528
	v_lshlrev_b64 v[166:167], 1, v[162:163]
	v_lshlrev_b64 v[178:179], 13, v[164:165]
	v_or_b32_e32 v176, 16, v164
	s_waitcnt vmcnt(11)
	v_fmamk_f32 v162, v177, 0x3a800000, v174
	v_mul_f32_e32 v163, 0x4f800000, v162
	v_cmp_gt_f32_e32 vcc, s75, v162
	v_ashrrev_i32_e32 v177, 31, v176
	s_nop 0
	v_cndmask_b32_e32 v165, v162, v163, vcc
	v_sqrt_f32_e32 v180, v165
	v_lshl_add_u64 v[162:163], s[22:23], 0, v[178:179]
	v_lshl_add_u64 v[162:163], v[162:163], 0, v[166:167]
	v_lshl_add_u64 v[178:179], v[176:177], 2, s[12:13]
	v_add_u32_e32 v181, -1, v180
	v_add_u32_e32 v182, 1, v180
	v_fma_f32 v183, -v181, v180, v165
	v_fma_f32 v184, -v182, v180, v165
	v_cmp_ge_f32_e64 s[4:5], 0, v183
	s_nop 1
	v_cndmask_b32_e64 v180, v180, v181, s[4:5]
	v_cmp_lt_f32_e64 s[4:5], 0, v184
	s_nop 1
	v_cndmask_b32_e64 v180, v180, v182, s[4:5]
	v_mul_f32_e32 v181, 0x37800000, v180
	v_cndmask_b32_e32 v180, v180, v181, vcc
	v_cmp_class_f32_e32 vcc, v165, v175
	s_nop 1
	v_cndmask_b32_e32 v165, v180, v165, vcc
	v_div_scale_f32 v180, s[4:5], v165, v165, 1.0
	v_rcp_f32_e32 v181, v180
	v_div_scale_f32 v182, vcc, 1.0, v165, 1.0
	v_fma_f32 v183, -v180, v181, 1.0
	v_fmac_f32_e32 v181, v183, v181
	v_mul_f32_e32 v183, v182, v181
	v_fma_f32 v184, -v180, v183, v182
	v_fmac_f32_e32 v183, v184, v181
	v_fma_f32 v180, -v180, v183, v182
	v_div_fmas_f32 v180, v180, v181, v183
	v_div_fixup_f32 v180, v180, v165, 1.0
	s_waitcnt vmcnt(0)
	v_pk_fma_f32 v[142:143], v[142:143], v[180:181], v[102:103] op_sel_hi:[1,0,1]
	v_pk_fma_f32 v[140:141], v[140:141], v[180:181], v[100:101] op_sel_hi:[1,0,1]
	v_pk_fma_f32 v[138:139], v[138:139], v[180:181], v[98:99] op_sel_hi:[1,0,1]
	v_pk_fma_f32 v[136:137], v[136:137], v[180:181], v[96:97] op_sel_hi:[1,0,1]
	v_pk_fma_f32 v[134:135], v[134:135], v[180:181], v[94:95] op_sel_hi:[1,0,1]
	v_pk_fma_f32 v[132:133], v[132:133], v[180:181], v[92:93] op_sel_hi:[1,0,1]
	v_pk_fma_f32 v[130:131], v[130:131], v[180:181], v[90:91] op_sel_hi:[1,0,1]
	v_pk_fma_f32 v[128:129], v[128:129], v[180:181], v[88:89] op_sel_hi:[1,0,1]
	v_max_f32_e32 v140, 0, v140
	v_max_f32_e32 v136, 0, v136
	v_max_f32_e32 v141, 0, v141
	v_max_f32_e32 v137, 0, v137
	v_max_f32_e32 v142, 0, v142
	v_max_f32_e32 v138, 0, v138
	v_max_f32_e32 v143, 0, v143
	v_max_f32_e32 v139, 0, v139
	v_max_f32_e32 v132, 0, v132
	v_max_f32_e32 v128, 0, v128
	v_max_f32_e32 v133, 0, v133
	v_max_f32_e32 v129, 0, v129
	v_max_f32_e32 v134, 0, v134
	v_max_f32_e32 v130, 0, v130
	v_max_f32_e32 v135, 0, v135
	v_max_f32_e32 v131, 0, v131
	v_pk_mul_f32 v[140:141], v[140:141], v[140:141]
	v_pk_mul_f32 v[136:137], v[136:137], v[136:137]
	v_pk_mul_f32 v[142:143], v[142:143], v[142:143]
	v_pk_mul_f32 v[138:139], v[138:139], v[138:139]
	v_pk_mul_f32 v[132:133], v[132:133], v[132:133]
	v_pk_mul_f32 v[180:181], v[128:129], v[128:129]
	v_pk_mul_f32 v[134:135], v[134:135], v[134:135]
	v_pk_mul_f32 v[182:183], v[130:131], v[130:131]
	v_cvt_pk_bf16_f32 v128, v140, v141
	v_cvt_pk_bf16_f32 v129, v142, v143
	v_cvt_pk_bf16_f32 v130, v136, v137
	v_cvt_pk_bf16_f32 v131, v138, v139
	v_cvt_pk_bf16_f32 v132, v132, v133
	v_cvt_pk_bf16_f32 v133, v134, v135
	v_cvt_pk_bf16_f32 v134, v180, v181
	v_cvt_pk_bf16_f32 v135, v182, v183
	global_store_dwordx4 v[162:163], v[128:131], off
	global_store_dwordx4 v[162:163], v[132:135], off offset:256
	s_nop 1
	v_mov_b32_e32 v130, v230
	v_or_b32_e32 v128, 32, v164
	v_ashrrev_i32_e32 v129, 31, v128
	v_lshl_add_u64 v[132:133], v[128:129], 2, s[12:13]
	s_nop 0
	v_fmamk_f32 v130, v130, 0x3a800000, v174
	v_mul_f32_e32 v131, 0x4f800000, v130
	v_cmp_gt_f32_e32 vcc, s75, v130
	s_nop 1
	v_cndmask_b32_e32 v134, v130, v131, vcc
	v_sqrt_f32_e32 v135, v134
	v_lshlrev_b64 v[130:131], 13, v[176:177]
	v_lshl_add_u64 v[130:131], s[22:23], 0, v[130:131]
	v_lshl_add_u64 v[130:131], v[130:131], 0, v[166:167]
	v_add_u32_e32 v136, -1, v135
	v_add_u32_e32 v137, 1, v135
	v_fma_f32 v138, -v136, v135, v134
	v_fma_f32 v139, -v137, v135, v134
	v_cmp_ge_f32_e64 s[4:5], 0, v138
	s_nop 1
	v_cndmask_b32_e64 v135, v135, v136, s[4:5]
	v_cmp_lt_f32_e64 s[4:5], 0, v139
	s_nop 1
	v_cndmask_b32_e64 v135, v135, v137, s[4:5]
	v_mul_f32_e32 v136, 0x37800000, v135
	v_cndmask_b32_e32 v135, v135, v136, vcc
	v_cmp_class_f32_e32 vcc, v134, v175
	s_nop 1
	v_cndmask_b32_e32 v134, v135, v134, vcc
	v_div_scale_f32 v135, s[4:5], v134, v134, 1.0
	v_rcp_f32_e32 v136, v135
	v_div_scale_f32 v137, vcc, 1.0, v134, 1.0
	v_fma_f32 v138, -v135, v136, 1.0
	v_fmac_f32_e32 v136, v138, v136
	v_mul_f32_e32 v138, v137, v136
	v_fma_f32 v139, -v135, v138, v137
	v_fmac_f32_e32 v138, v139, v136
	v_fma_f32 v135, -v135, v138, v137
	v_div_fmas_f32 v135, v135, v136, v138
	v_div_fixup_f32 v134, v135, v134, 1.0
	v_pk_fma_f32 v[126:127], v[126:127], v[134:135], v[102:103] op_sel_hi:[1,0,1]
	v_pk_fma_f32 v[124:125], v[124:125], v[134:135], v[100:101] op_sel_hi:[1,0,1]
	v_pk_fma_f32 v[122:123], v[122:123], v[134:135], v[98:99] op_sel_hi:[1,0,1]
	v_pk_fma_f32 v[120:121], v[120:121], v[134:135], v[96:97] op_sel_hi:[1,0,1]
	v_pk_fma_f32 v[118:119], v[118:119], v[134:135], v[94:95] op_sel_hi:[1,0,1]
	v_pk_fma_f32 v[116:117], v[116:117], v[134:135], v[92:93] op_sel_hi:[1,0,1]
	v_pk_fma_f32 v[114:115], v[114:115], v[134:135], v[90:91] op_sel_hi:[1,0,1]
	v_pk_fma_f32 v[112:113], v[112:113], v[134:135], v[88:89] op_sel_hi:[1,0,1]
	v_max_f32_e32 v124, 0, v124
	v_max_f32_e32 v120, 0, v120
	v_max_f32_e32 v125, 0, v125
	v_max_f32_e32 v121, 0, v121
	v_max_f32_e32 v126, 0, v126
	v_max_f32_e32 v122, 0, v122
	v_max_f32_e32 v127, 0, v127
	v_max_f32_e32 v123, 0, v123
	v_max_f32_e32 v116, 0, v116
	v_max_f32_e32 v112, 0, v112
	v_max_f32_e32 v117, 0, v117
	v_max_f32_e32 v113, 0, v113
	v_max_f32_e32 v118, 0, v118
	v_max_f32_e32 v114, 0, v114
	v_max_f32_e32 v119, 0, v119
	v_max_f32_e32 v115, 0, v115
	v_pk_mul_f32 v[124:125], v[124:125], v[124:125]
	v_pk_mul_f32 v[120:121], v[120:121], v[120:121]
	v_pk_mul_f32 v[126:127], v[126:127], v[126:127]
	v_pk_mul_f32 v[122:123], v[122:123], v[122:123]
	v_pk_mul_f32 v[116:117], v[116:117], v[116:117]
	v_pk_mul_f32 v[134:135], v[112:113], v[112:113]
	v_pk_mul_f32 v[118:119], v[118:119], v[118:119]
	v_pk_mul_f32 v[136:137], v[114:115], v[114:115]
	v_cvt_pk_bf16_f32 v112, v124, v125
	v_cvt_pk_bf16_f32 v113, v126, v127
	v_cvt_pk_bf16_f32 v114, v120, v121
	v_cvt_pk_bf16_f32 v115, v122, v123
	v_cvt_pk_bf16_f32 v116, v116, v117
	v_cvt_pk_bf16_f32 v117, v118, v119
	v_cvt_pk_bf16_f32 v118, v134, v135
	v_cvt_pk_bf16_f32 v119, v136, v137
	global_store_dwordx4 v[130:131], v[112:115], off
	global_store_dwordx4 v[130:131], v[116:119], off offset:256
	s_nop 1
	v_mov_b32_e32 v114, v231
	v_or_b32_e32 v112, 48, v164
	v_ashrrev_i32_e32 v113, 31, v112
	v_lshl_add_u64 v[116:117], v[112:113], 2, s[12:13]
	s_nop 0
	v_fmamk_f32 v114, v114, 0x3a800000, v174
	v_mul_f32_e32 v115, 0x4f800000, v114
	v_cmp_gt_f32_e32 vcc, s75, v114
	s_nop 1
	v_cndmask_b32_e32 v118, v114, v115, vcc
	v_sqrt_f32_e32 v119, v118
	v_lshlrev_b64 v[114:115], 13, v[128:129]
	v_lshl_add_u64 v[114:115], s[22:23], 0, v[114:115]
	v_lshl_add_u64 v[114:115], v[114:115], 0, v[166:167]
	v_add_u32_e32 v120, -1, v119
	v_add_u32_e32 v121, 1, v119
	v_fma_f32 v122, -v120, v119, v118
	v_fma_f32 v123, -v121, v119, v118
	v_cmp_ge_f32_e64 s[4:5], 0, v122
	s_nop 1
	v_cndmask_b32_e64 v119, v119, v120, s[4:5]
	v_cmp_lt_f32_e64 s[4:5], 0, v123
	s_nop 1
	v_cndmask_b32_e64 v119, v119, v121, s[4:5]
	v_mul_f32_e32 v120, 0x37800000, v119
	v_cndmask_b32_e32 v119, v119, v120, vcc
	v_cmp_class_f32_e32 vcc, v118, v175
	s_nop 1
	v_cndmask_b32_e32 v118, v119, v118, vcc
	v_div_scale_f32 v119, s[4:5], v118, v118, 1.0
	v_rcp_f32_e32 v120, v119
	v_div_scale_f32 v121, vcc, 1.0, v118, 1.0
	v_fma_f32 v122, -v119, v120, 1.0
	v_fmac_f32_e32 v120, v122, v120
	v_mul_f32_e32 v122, v121, v120
	v_fma_f32 v123, -v119, v122, v121
	v_fmac_f32_e32 v122, v123, v120
	v_fma_f32 v119, -v119, v122, v121
	v_div_fmas_f32 v119, v119, v120, v122
	v_div_fixup_f32 v118, v119, v118, 1.0
	v_pk_fma_f32 v[110:111], v[110:111], v[118:119], v[102:103] op_sel_hi:[1,0,1]
	v_pk_fma_f32 v[108:109], v[108:109], v[118:119], v[100:101] op_sel_hi:[1,0,1]
	v_pk_fma_f32 v[106:107], v[106:107], v[118:119], v[98:99] op_sel_hi:[1,0,1]
	v_pk_fma_f32 v[104:105], v[104:105], v[118:119], v[96:97] op_sel_hi:[1,0,1]
	v_pk_fma_f32 v[86:87], v[86:87], v[118:119], v[94:95] op_sel_hi:[1,0,1]
	v_pk_fma_f32 v[84:85], v[84:85], v[118:119], v[92:93] op_sel_hi:[1,0,1]
	v_pk_fma_f32 v[82:83], v[82:83], v[118:119], v[90:91] op_sel_hi:[1,0,1]
	v_pk_fma_f32 v[80:81], v[80:81], v[118:119], v[88:89] op_sel_hi:[1,0,1]
	v_max_f32_e32 v108, 0, v108
	v_max_f32_e32 v104, 0, v104
	v_max_f32_e32 v109, 0, v109
	v_max_f32_e32 v105, 0, v105
	v_max_f32_e32 v110, 0, v110
	v_max_f32_e32 v106, 0, v106
	v_max_f32_e32 v111, 0, v111
	v_max_f32_e32 v107, 0, v107
	v_max_f32_e32 v84, 0, v84
	v_max_f32_e32 v80, 0, v80
	v_max_f32_e32 v85, 0, v85
	v_max_f32_e32 v81, 0, v81
	v_max_f32_e32 v86, 0, v86
	v_max_f32_e32 v82, 0, v82
	v_max_f32_e32 v87, 0, v87
	v_max_f32_e32 v83, 0, v83
	v_pk_mul_f32 v[108:109], v[108:109], v[108:109]
	v_pk_mul_f32 v[104:105], v[104:105], v[104:105]
	v_pk_mul_f32 v[110:111], v[110:111], v[110:111]
	v_pk_mul_f32 v[106:107], v[106:107], v[106:107]
	v_pk_mul_f32 v[84:85], v[84:85], v[84:85]
	v_pk_mul_f32 v[118:119], v[80:81], v[80:81]
	v_pk_mul_f32 v[86:87], v[86:87], v[86:87]
	v_pk_mul_f32 v[120:121], v[82:83], v[82:83]
	v_cvt_pk_bf16_f32 v80, v108, v109
	v_cvt_pk_bf16_f32 v81, v110, v111
	v_cvt_pk_bf16_f32 v82, v104, v105
	v_cvt_pk_bf16_f32 v83, v106, v107
	v_cvt_pk_bf16_f32 v84, v84, v85
	v_cvt_pk_bf16_f32 v85, v86, v87
	v_cvt_pk_bf16_f32 v86, v118, v119
	v_cvt_pk_bf16_f32 v87, v120, v121
	global_store_dwordx4 v[114:115], v[80:83], off
	global_store_dwordx4 v[114:115], v[84:87], off offset:256
	s_nop 1
	v_mov_b32_e32 v80, v232
	s_nop 0
	v_fmamk_f32 v80, v80, 0x3a800000, v174
	v_mul_f32_e32 v81, 0x4f800000, v80
	v_cmp_gt_f32_e32 vcc, s75, v80
	s_nop 1
	v_cndmask_b32_e32 v82, v80, v81, vcc
	v_sqrt_f32_e32 v83, v82
	v_lshlrev_b64 v[80:81], 13, v[112:113]
	v_lshl_add_u64 v[80:81], s[22:23], 0, v[80:81]
	v_lshl_add_u64 v[80:81], v[80:81], 0, v[166:167]
	v_add_u32_e32 v84, -1, v83
	v_add_u32_e32 v85, 1, v83
	v_fma_f32 v86, -v84, v83, v82
	v_fma_f32 v87, -v85, v83, v82
	v_cmp_ge_f32_e64 s[4:5], 0, v86
	s_nop 1
	v_cndmask_b32_e64 v83, v83, v84, s[4:5]
	v_cmp_lt_f32_e64 s[4:5], 0, v87
	s_nop 1
	v_cndmask_b32_e64 v83, v83, v85, s[4:5]
	v_mul_f32_e32 v84, 0x37800000, v83
	v_cndmask_b32_e32 v83, v83, v84, vcc
	v_cmp_class_f32_e32 vcc, v82, v175
	s_nop 1
	v_cndmask_b32_e32 v82, v83, v82, vcc
	v_div_scale_f32 v83, s[4:5], v82, v82, 1.0
	v_rcp_f32_e32 v84, v83
	v_div_scale_f32 v85, vcc, 1.0, v82, 1.0
	v_fma_f32 v86, -v83, v84, 1.0
	v_fmac_f32_e32 v84, v86, v84
	v_mul_f32_e32 v86, v85, v84
	v_fma_f32 v87, -v83, v86, v85
	v_fmac_f32_e32 v86, v87, v84
	v_fma_f32 v83, -v83, v86, v85
	v_div_fmas_f32 v83, v83, v84, v86
	v_div_fixup_f32 v82, v83, v82, 1.0
	v_pk_fma_f32 v[78:79], v[78:79], v[82:83], v[102:103] op_sel_hi:[1,0,1]
	v_pk_fma_f32 v[76:77], v[76:77], v[82:83], v[100:101] op_sel_hi:[1,0,1]
	v_pk_fma_f32 v[74:75], v[74:75], v[82:83], v[98:99] op_sel_hi:[1,0,1]
	v_pk_fma_f32 v[72:73], v[72:73], v[82:83], v[96:97] op_sel_hi:[1,0,1]
	v_pk_fma_f32 v[70:71], v[70:71], v[82:83], v[94:95] op_sel_hi:[1,0,1]
	v_pk_fma_f32 v[68:69], v[68:69], v[82:83], v[92:93] op_sel_hi:[1,0,1]
	v_pk_fma_f32 v[66:67], v[66:67], v[82:83], v[90:91] op_sel_hi:[1,0,1]
	v_pk_fma_f32 v[64:65], v[64:65], v[82:83], v[88:89] op_sel_hi:[1,0,1]
	v_max_f32_e32 v76, 0, v76
	v_max_f32_e32 v72, 0, v72
	v_max_f32_e32 v77, 0, v77
	v_max_f32_e32 v73, 0, v73
	v_max_f32_e32 v78, 0, v78
	v_max_f32_e32 v74, 0, v74
	v_max_f32_e32 v79, 0, v79
	v_max_f32_e32 v75, 0, v75
	v_max_f32_e32 v68, 0, v68
	v_max_f32_e32 v64, 0, v64
	v_max_f32_e32 v69, 0, v69
	v_max_f32_e32 v65, 0, v65
	v_max_f32_e32 v70, 0, v70
	v_max_f32_e32 v66, 0, v66
	v_max_f32_e32 v71, 0, v71
	v_max_f32_e32 v67, 0, v67
	v_pk_mul_f32 v[76:77], v[76:77], v[76:77]
	v_pk_mul_f32 v[72:73], v[72:73], v[72:73]
	v_pk_mul_f32 v[78:79], v[78:79], v[78:79]
	v_pk_mul_f32 v[74:75], v[74:75], v[74:75]
	v_pk_mul_f32 v[68:69], v[68:69], v[68:69]
	v_pk_mul_f32 v[82:83], v[64:65], v[64:65]
	v_pk_mul_f32 v[70:71], v[70:71], v[70:71]
	v_pk_mul_f32 v[84:85], v[66:67], v[66:67]
	v_cvt_pk_bf16_f32 v64, v76, v77
	v_cvt_pk_bf16_f32 v65, v78, v79
	v_cvt_pk_bf16_f32 v66, v72, v73
	v_cvt_pk_bf16_f32 v67, v74, v75
	v_cvt_pk_bf16_f32 v68, v68, v69
	v_cvt_pk_bf16_f32 v69, v70, v71
	v_cvt_pk_bf16_f32 v70, v82, v83
	v_cvt_pk_bf16_f32 v71, v84, v85
	global_store_dwordx4 v[80:81], v[64:67], off
	global_store_dwordx4 v[80:81], v[68:71], off offset:256
	s_nop 1
	v_mov_b32_e32 v64, v233
	s_nop 0
	v_fmamk_f32 v64, v64, 0x3a800000, v174
	v_mul_f32_e32 v65, 0x4f800000, v64
	v_cmp_gt_f32_e32 vcc, s75, v64
	s_nop 1
	v_cndmask_b32_e32 v66, v64, v65, vcc
	v_sqrt_f32_e32 v67, v66
	v_lshl_add_u64 v[64:65], v[162:163], 0, s[20:21]
	v_add_u32_e32 v68, -1, v67
	v_add_u32_e32 v69, 1, v67
	v_fma_f32 v70, -v68, v67, v66
	v_fma_f32 v71, -v69, v67, v66
	v_cmp_ge_f32_e64 s[4:5], 0, v70
	s_nop 1
	v_cndmask_b32_e64 v67, v67, v68, s[4:5]
	v_cmp_lt_f32_e64 s[4:5], 0, v71
	s_nop 1
	v_cndmask_b32_e64 v67, v67, v69, s[4:5]
	v_mul_f32_e32 v68, 0x37800000, v67
	v_cndmask_b32_e32 v67, v67, v68, vcc
	v_cmp_class_f32_e32 vcc, v66, v175
	s_nop 1
	v_cndmask_b32_e32 v68, v67, v66, vcc
	v_div_scale_f32 v69, s[4:5], v68, v68, 1.0
	v_rcp_f32_e32 v70, v69
	v_add_co_u32_e32 v66, vcc, s76, v162
	v_fma_f32 v72, -v69, v70, 1.0
	s_nop 0
	v_addc_co_u32_e32 v67, vcc, 0, v163, vcc
	v_div_scale_f32 v71, vcc, 1.0, v68, 1.0
	v_fmac_f32_e32 v70, v72, v70
	v_mul_f32_e32 v72, v71, v70
	v_fma_f32 v73, -v69, v72, v71
	v_fmac_f32_e32 v72, v73, v70
	v_fma_f32 v69, -v69, v72, v71
	v_div_fmas_f32 v69, v69, v70, v72
	v_div_fixup_f32 v68, v69, v68, 1.0
	v_pk_fma_f32 v[62:63], v[62:63], v[68:69], v[102:103] op_sel_hi:[1,0,1]
	v_pk_fma_f32 v[60:61], v[60:61], v[68:69], v[100:101] op_sel_hi:[1,0,1]
	v_pk_fma_f32 v[58:59], v[58:59], v[68:69], v[98:99] op_sel_hi:[1,0,1]
	v_pk_fma_f32 v[56:57], v[56:57], v[68:69], v[96:97] op_sel_hi:[1,0,1]
	v_pk_fma_f32 v[54:55], v[54:55], v[68:69], v[94:95] op_sel_hi:[1,0,1]
	v_pk_fma_f32 v[52:53], v[52:53], v[68:69], v[92:93] op_sel_hi:[1,0,1]
	v_pk_fma_f32 v[50:51], v[50:51], v[68:69], v[90:91] op_sel_hi:[1,0,1]
	v_pk_fma_f32 v[48:49], v[48:49], v[68:69], v[88:89] op_sel_hi:[1,0,1]
	v_max_f32_e32 v60, 0, v60
	v_max_f32_e32 v56, 0, v56
	v_max_f32_e32 v61, 0, v61
	v_max_f32_e32 v57, 0, v57
	v_max_f32_e32 v62, 0, v62
	v_max_f32_e32 v58, 0, v58
	v_max_f32_e32 v63, 0, v63
	v_max_f32_e32 v59, 0, v59
	v_max_f32_e32 v52, 0, v52
	v_max_f32_e32 v48, 0, v48
	v_max_f32_e32 v53, 0, v53
	v_max_f32_e32 v49, 0, v49
	v_max_f32_e32 v54, 0, v54
	v_max_f32_e32 v50, 0, v50
	v_max_f32_e32 v55, 0, v55
	v_max_f32_e32 v51, 0, v51
	v_pk_mul_f32 v[60:61], v[60:61], v[60:61]
	v_pk_mul_f32 v[56:57], v[56:57], v[56:57]
	v_pk_mul_f32 v[62:63], v[62:63], v[62:63]
	v_pk_mul_f32 v[58:59], v[58:59], v[58:59]
	v_pk_mul_f32 v[52:53], v[52:53], v[52:53]
	v_pk_mul_f32 v[68:69], v[48:49], v[48:49]
	v_pk_mul_f32 v[54:55], v[54:55], v[54:55]
	v_pk_mul_f32 v[70:71], v[50:51], v[50:51]
	v_cvt_pk_bf16_f32 v48, v60, v61
	v_cvt_pk_bf16_f32 v49, v62, v63
	v_cvt_pk_bf16_f32 v50, v56, v57
	v_cvt_pk_bf16_f32 v51, v58, v59
	v_cvt_pk_bf16_f32 v52, v52, v53
	v_cvt_pk_bf16_f32 v53, v54, v55
	v_cvt_pk_bf16_f32 v54, v68, v69
	v_cvt_pk_bf16_f32 v55, v70, v71
	global_store_dwordx4 v[66:67], v[48:51], off
	global_store_dwordx4 v[64:65], v[52:55], off offset:256
	s_nop 1
	v_mov_b32_e32 v48, v234
	s_nop 0
	v_fmamk_f32 v48, v48, 0x3a800000, v174
	v_mul_f32_e32 v49, 0x4f800000, v48
	v_cmp_gt_f32_e32 vcc, s75, v48
	s_nop 1
	v_cndmask_b32_e32 v50, v48, v49, vcc
	v_sqrt_f32_e32 v51, v50
	v_lshl_add_u64 v[48:49], v[162:163], 0, s[24:25]
	v_add_u32_e32 v52, -1, v51
	v_add_u32_e32 v53, 1, v51
	v_fma_f32 v54, -v52, v51, v50
	v_fma_f32 v55, -v53, v51, v50
	v_cmp_ge_f32_e64 s[4:5], 0, v54
	s_nop 1
	v_cndmask_b32_e64 v51, v51, v52, s[4:5]
	v_cmp_lt_f32_e64 s[4:5], 0, v55
	s_nop 1
	v_cndmask_b32_e64 v51, v51, v53, s[4:5]
	v_mul_f32_e32 v52, 0x37800000, v51
	v_cndmask_b32_e32 v51, v51, v52, vcc
	v_cmp_class_f32_e32 vcc, v50, v175
	s_nop 1
	v_cndmask_b32_e32 v52, v51, v50, vcc
	v_div_scale_f32 v53, s[4:5], v52, v52, 1.0
	v_rcp_f32_e32 v54, v53
	v_add_co_u32_e32 v50, vcc, s77, v162
	v_fma_f32 v56, -v53, v54, 1.0
	s_nop 0
	v_addc_co_u32_e32 v51, vcc, 0, v163, vcc
	v_div_scale_f32 v55, vcc, 1.0, v52, 1.0
	v_fmac_f32_e32 v54, v56, v54
	v_mul_f32_e32 v56, v55, v54
	v_fma_f32 v57, -v53, v56, v55
	v_fmac_f32_e32 v56, v57, v54
	v_fma_f32 v53, -v53, v56, v55
	v_div_fmas_f32 v53, v53, v54, v56
	v_div_fixup_f32 v52, v53, v52, 1.0
	v_pk_fma_f32 v[46:47], v[46:47], v[52:53], v[102:103] op_sel_hi:[1,0,1]
	v_pk_fma_f32 v[44:45], v[44:45], v[52:53], v[100:101] op_sel_hi:[1,0,1]
	v_pk_fma_f32 v[42:43], v[42:43], v[52:53], v[98:99] op_sel_hi:[1,0,1]
	v_pk_fma_f32 v[40:41], v[40:41], v[52:53], v[96:97] op_sel_hi:[1,0,1]
	v_pk_fma_f32 v[38:39], v[38:39], v[52:53], v[94:95] op_sel_hi:[1,0,1]
	v_pk_fma_f32 v[36:37], v[36:37], v[52:53], v[92:93] op_sel_hi:[1,0,1]
	v_pk_fma_f32 v[34:35], v[34:35], v[52:53], v[90:91] op_sel_hi:[1,0,1]
	v_pk_fma_f32 v[32:33], v[32:33], v[52:53], v[88:89] op_sel_hi:[1,0,1]
	v_max_f32_e32 v44, 0, v44
	v_max_f32_e32 v40, 0, v40
	v_max_f32_e32 v45, 0, v45
	v_max_f32_e32 v41, 0, v41
	v_max_f32_e32 v46, 0, v46
	v_max_f32_e32 v42, 0, v42
	v_max_f32_e32 v47, 0, v47
	v_max_f32_e32 v43, 0, v43
	v_max_f32_e32 v36, 0, v36
	v_max_f32_e32 v32, 0, v32
	v_max_f32_e32 v37, 0, v37
	v_max_f32_e32 v33, 0, v33
	v_max_f32_e32 v38, 0, v38
	v_max_f32_e32 v34, 0, v34
	v_max_f32_e32 v39, 0, v39
	v_max_f32_e32 v35, 0, v35
	v_pk_mul_f32 v[44:45], v[44:45], v[44:45]
	v_pk_mul_f32 v[40:41], v[40:41], v[40:41]
	v_pk_mul_f32 v[46:47], v[46:47], v[46:47]
	v_pk_mul_f32 v[42:43], v[42:43], v[42:43]
	v_pk_mul_f32 v[36:37], v[36:37], v[36:37]
	v_pk_mul_f32 v[52:53], v[32:33], v[32:33]
	v_pk_mul_f32 v[38:39], v[38:39], v[38:39]
	v_pk_mul_f32 v[54:55], v[34:35], v[34:35]
	v_cvt_pk_bf16_f32 v32, v44, v45
	v_cvt_pk_bf16_f32 v33, v46, v47
	v_cvt_pk_bf16_f32 v34, v40, v41
	v_cvt_pk_bf16_f32 v35, v42, v43
	v_cvt_pk_bf16_f32 v36, v36, v37
	v_cvt_pk_bf16_f32 v37, v38, v39
	v_cvt_pk_bf16_f32 v38, v52, v53
	v_cvt_pk_bf16_f32 v39, v54, v55
	global_store_dwordx4 v[50:51], v[32:35], off
	global_store_dwordx4 v[48:49], v[36:39], off offset:256
	s_nop 1
	v_mov_b32_e32 v32, v235
	s_nop 0
	v_fmamk_f32 v32, v32, 0x3a800000, v174
	v_mul_f32_e32 v33, 0x4f800000, v32
	v_cmp_gt_f32_e32 vcc, s75, v32
	s_nop 1
	v_cndmask_b32_e32 v34, v32, v33, vcc
	v_sqrt_f32_e32 v35, v34
	v_lshl_add_u64 v[32:33], v[162:163], 0, s[26:27]
	v_add_u32_e32 v36, -1, v35
	v_add_u32_e32 v37, 1, v35
	v_fma_f32 v38, -v36, v35, v34
	v_fma_f32 v39, -v37, v35, v34
	v_cmp_ge_f32_e64 s[4:5], 0, v38
	s_nop 1
	v_cndmask_b32_e64 v35, v35, v36, s[4:5]
	v_cmp_lt_f32_e64 s[4:5], 0, v39
	s_nop 1
	v_cndmask_b32_e64 v35, v35, v37, s[4:5]
	v_mul_f32_e32 v36, 0x37800000, v35
	v_cndmask_b32_e32 v35, v35, v36, vcc
	v_cmp_class_f32_e32 vcc, v34, v175
	s_nop 1
	v_cndmask_b32_e32 v36, v35, v34, vcc
	v_div_scale_f32 v37, s[4:5], v36, v36, 1.0
	v_rcp_f32_e32 v38, v37
	v_add_co_u32_e32 v34, vcc, s78, v162
	v_fma_f32 v40, -v37, v38, 1.0
	s_nop 0
	v_addc_co_u32_e32 v35, vcc, 0, v163, vcc
	v_div_scale_f32 v39, vcc, 1.0, v36, 1.0
	v_fmac_f32_e32 v38, v40, v38
	v_mul_f32_e32 v40, v39, v38
	v_fma_f32 v41, -v37, v40, v39
	v_fmac_f32_e32 v40, v41, v38
	v_fma_f32 v37, -v37, v40, v39
	v_div_fmas_f32 v37, v37, v38, v40
	v_div_fixup_f32 v36, v37, v36, 1.0
	v_pk_fma_f32 v[30:31], v[30:31], v[36:37], v[102:103] op_sel_hi:[1,0,1]
	v_pk_fma_f32 v[28:29], v[28:29], v[36:37], v[100:101] op_sel_hi:[1,0,1]
	v_pk_fma_f32 v[26:27], v[26:27], v[36:37], v[98:99] op_sel_hi:[1,0,1]
	v_pk_fma_f32 v[24:25], v[24:25], v[36:37], v[96:97] op_sel_hi:[1,0,1]
	v_pk_fma_f32 v[22:23], v[22:23], v[36:37], v[94:95] op_sel_hi:[1,0,1]
	v_pk_fma_f32 v[20:21], v[20:21], v[36:37], v[92:93] op_sel_hi:[1,0,1]
	v_pk_fma_f32 v[18:19], v[18:19], v[36:37], v[90:91] op_sel_hi:[1,0,1]
	v_pk_fma_f32 v[16:17], v[16:17], v[36:37], v[88:89] op_sel_hi:[1,0,1]
	v_max_f32_e32 v28, 0, v28
	v_max_f32_e32 v24, 0, v24
	v_max_f32_e32 v29, 0, v29
	v_max_f32_e32 v25, 0, v25
	v_max_f32_e32 v30, 0, v30
	v_max_f32_e32 v26, 0, v26
	v_max_f32_e32 v31, 0, v31
	v_max_f32_e32 v27, 0, v27
	v_max_f32_e32 v20, 0, v20
	v_max_f32_e32 v16, 0, v16
	v_max_f32_e32 v21, 0, v21
	v_max_f32_e32 v17, 0, v17
	v_max_f32_e32 v22, 0, v22
	v_max_f32_e32 v18, 0, v18
	v_max_f32_e32 v23, 0, v23
	v_max_f32_e32 v19, 0, v19
	v_pk_mul_f32 v[28:29], v[28:29], v[28:29]
	v_pk_mul_f32 v[24:25], v[24:25], v[24:25]
	v_pk_mul_f32 v[30:31], v[30:31], v[30:31]
	v_pk_mul_f32 v[26:27], v[26:27], v[26:27]
	v_pk_mul_f32 v[20:21], v[20:21], v[20:21]
	v_pk_mul_f32 v[36:37], v[16:17], v[16:17]
	v_pk_mul_f32 v[22:23], v[22:23], v[22:23]
	v_pk_mul_f32 v[38:39], v[18:19], v[18:19]
	v_cvt_pk_bf16_f32 v16, v28, v29
	v_cvt_pk_bf16_f32 v17, v30, v31
	v_cvt_pk_bf16_f32 v18, v24, v25
	v_cvt_pk_bf16_f32 v19, v26, v27
	v_cvt_pk_bf16_f32 v20, v20, v21
	v_cvt_pk_bf16_f32 v21, v22, v23
	v_cvt_pk_bf16_f32 v22, v36, v37
	v_cvt_pk_bf16_f32 v23, v38, v39
	global_store_dwordx4 v[34:35], v[16:19], off
	global_store_dwordx4 v[32:33], v[20:23], off offset:256
	s_nop 1
	v_mov_b32_e32 v16, v236
	s_nop 0
	v_fmamk_f32 v16, v16, 0x3a800000, v174
	v_mul_f32_e32 v17, 0x4f800000, v16
	v_cmp_gt_f32_e32 vcc, s75, v16
	s_nop 1
	v_cndmask_b32_e32 v18, v16, v17, vcc
	v_sqrt_f32_e32 v19, v18
	v_lshl_add_u64 v[16:17], v[162:163], 0, s[28:29]
	v_add_u32_e32 v20, -1, v19
	v_add_u32_e32 v21, 1, v19
	v_fma_f32 v22, -v20, v19, v18
	v_fma_f32 v23, -v21, v19, v18
	v_cmp_ge_f32_e64 s[4:5], 0, v22
	s_nop 1
	v_cndmask_b32_e64 v19, v19, v20, s[4:5]
	v_cmp_lt_f32_e64 s[4:5], 0, v23
	s_nop 1
	v_cndmask_b32_e64 v19, v19, v21, s[4:5]
	v_mul_f32_e32 v20, 0x37800000, v19
	v_cndmask_b32_e32 v19, v19, v20, vcc
	v_cmp_class_f32_e32 vcc, v18, v175
	s_nop 1
	v_cndmask_b32_e32 v20, v19, v18, vcc
	v_div_scale_f32 v21, s[4:5], v20, v20, 1.0
	v_rcp_f32_e32 v22, v21
	v_add_co_u32_e32 v18, vcc, s79, v162
	v_fma_f32 v24, -v21, v22, 1.0
	s_nop 0
	v_addc_co_u32_e32 v19, vcc, 0, v163, vcc
	v_div_scale_f32 v23, vcc, 1.0, v20, 1.0
	v_fmac_f32_e32 v22, v24, v22
	v_mul_f32_e32 v24, v23, v22
	v_fma_f32 v25, -v21, v24, v23
	v_fmac_f32_e32 v24, v25, v22
	v_fma_f32 v21, -v21, v24, v23
	v_div_fmas_f32 v21, v21, v22, v24
	v_div_fixup_f32 v20, v21, v20, 1.0
	v_pk_fma_f32 v[14:15], v[14:15], v[20:21], v[102:103] op_sel_hi:[1,0,1]
	v_pk_fma_f32 v[12:13], v[12:13], v[20:21], v[100:101] op_sel_hi:[1,0,1]
	v_pk_fma_f32 v[10:11], v[10:11], v[20:21], v[98:99] op_sel_hi:[1,0,1]
	v_pk_fma_f32 v[8:9], v[8:9], v[20:21], v[96:97] op_sel_hi:[1,0,1]
	v_pk_fma_f32 v[6:7], v[6:7], v[20:21], v[94:95] op_sel_hi:[1,0,1]
	v_pk_fma_f32 v[4:5], v[4:5], v[20:21], v[92:93] op_sel_hi:[1,0,1]
	v_pk_fma_f32 v[2:3], v[2:3], v[20:21], v[90:91] op_sel_hi:[1,0,1]
	v_pk_fma_f32 v[0:1], v[0:1], v[20:21], v[88:89] op_sel_hi:[1,0,1]
	v_max_f32_e32 v12, 0, v12
	v_max_f32_e32 v8, 0, v8
	v_max_f32_e32 v13, 0, v13
	v_max_f32_e32 v9, 0, v9
	v_max_f32_e32 v14, 0, v14
	v_max_f32_e32 v10, 0, v10
	v_max_f32_e32 v15, 0, v15
	v_max_f32_e32 v11, 0, v11
	v_max_f32_e32 v4, 0, v4
	v_max_f32_e32 v0, 0, v0
	v_max_f32_e32 v5, 0, v5
	v_max_f32_e32 v1, 0, v1
	v_max_f32_e32 v6, 0, v6
	v_max_f32_e32 v2, 0, v2
	v_max_f32_e32 v7, 0, v7
	v_max_f32_e32 v3, 0, v3
	v_pk_mul_f32 v[12:13], v[12:13], v[12:13]
	v_pk_mul_f32 v[8:9], v[8:9], v[8:9]
	v_pk_mul_f32 v[14:15], v[14:15], v[14:15]
	v_pk_mul_f32 v[10:11], v[10:11], v[10:11]
	s_andn2_b64 vcc, exec, s[0:1]
	v_pk_mul_f32 v[4:5], v[4:5], v[4:5]
	v_pk_mul_f32 v[20:21], v[0:1], v[0:1]
	v_pk_mul_f32 v[6:7], v[6:7], v[6:7]
	v_pk_mul_f32 v[22:23], v[2:3], v[2:3]
	v_cvt_pk_bf16_f32 v0, v12, v13
	v_cvt_pk_bf16_f32 v1, v14, v15
	v_cvt_pk_bf16_f32 v2, v8, v9
	v_cvt_pk_bf16_f32 v3, v10, v11
	s_mov_b64 s[0:1], -1
	v_cvt_pk_bf16_f32 v4, v4, v5
	v_cvt_pk_bf16_f32 v5, v6, v7
	v_cvt_pk_bf16_f32 v6, v20, v21
	v_cvt_pk_bf16_f32 v7, v22, v23
	global_store_dwordx4 v[18:19], v[0:3], off
	global_store_dwordx4 v[16:17], v[4:7], off offset:256
	s_cbranch_vccnz .LBB0_745
	s_andn2_b64 vcc, exec, s[8:9]
	s_cbranch_vccnz .LBB0_744
	s_barrier
	s_branch .LBB0_744
